# ssd_local chunk-state stores staged through per-wave LDS slice into 16-byte coalesced stores (64 store_short -> 8 dwordx4 per lane)
# speedup vs baseline: 1.0065x; 1.0003x over previous
.LBB0_518:
	s_or_b64 exec, exec, s[0:1]
	v_mov_b32_e32 v85, v206
	s_mov_b32 s0, 0x20500
	s_waitcnt lgkmcnt(0)
	s_barrier
	v_mov_b32_e32 v0, 0x3f0
	v_ashrrev_i32_e32 v82, 8, v85
	v_bfe_u32 v83, v85, 6, 2
	v_cmp_gt_u32_e32 vcc, s57, v85
	s_addk_i32 s0, 0x100
	v_lshl_add_u32 v1, v82, 10, s0
	v_cndmask_b32_e32 v0, 0, v0, vcc
	v_lshlrev_b32_e32 v2, 2, v83
	v_add3_u32 v0, v1, v0, v2
	v_lshlrev_b32_e32 v2, 1, v85
	s_mov_b32 s1, 0x3fffff20
	v_and_b32_e32 v84, 62, v2
	v_and_or_b32 v2, v85, s1, v83
	v_lshlrev_b32_e32 v64, 2, v2
	s_mov_b32 s1, 0x20d00
	s_addk_i32 s1, 0x100
	v_or_b32_e32 v4, 16, v64
	v_add_u32_e32 v2, s0, v64
	v_add_u32_e32 v3, s1, v64
	v_add_u32_e32 v5, s0, v4
	v_add_u32_e32 v4, s1, v4
	v_or_b32_e32 v6, 32, v64
	v_or_b32_e32 v10, 48, v64
	v_add_u32_e32 v7, s0, v6
	v_add_u32_e32 v6, s1, v6
	v_add_u32_e32 v8, s0, v10
	ds_read_b32 v80, v0
	ds_read_b32 v0, v2
	ds_read_b32 v18, v3
	ds_read_b32 v2, v5
	ds_read_b32 v19, v4
	ds_read_b32 v3, v7
	ds_read_b32 v4, v6
	ds_read_b32 v5, v8
	s_waitcnt lgkmcnt(6)
	v_sub_f32_e32 v0, v80, v0
	v_mul_f32_e32 v0, 0x3fb8aa3b, v0
	v_exp_f32_e32 v20, v0
	s_waitcnt lgkmcnt(4)
	v_sub_f32_e32 v0, v80, v2
	v_mul_f32_e32 v0, 0x3fb8aa3b, v0
	v_exp_f32_e32 v21, v0
	s_waitcnt lgkmcnt(2)
	v_sub_f32_e32 v0, v80, v3
	v_mul_f32_e32 v0, 0x3fb8aa3b, v0
	v_exp_f32_e32 v8, v0
	s_waitcnt lgkmcnt(0)
	v_sub_f32_e32 v0, v80, v5
	v_or_b32_e32 v5, 0x50, v64
	v_mul_f32_e32 v0, 0x3fb8aa3b, v0
	v_or_b32_e32 v2, 64, v64
	v_add_u32_e32 v6, s0, v5
	v_add_u32_e32 v7, s1, v5
	v_or_b32_e32 v5, 0x60, v64
	v_exp_f32_e32 v9, v0
	v_add_u32_e32 v0, s1, v10
	v_add_u32_e32 v3, s0, v2
	v_add_u32_e32 v2, s1, v2
	v_add_u32_e32 v10, s0, v5
	v_or_b32_e32 v22, 0x70, v64
	v_add_u32_e32 v11, s1, v5
	v_add_u32_e32 v14, s0, v22
	ds_read_b32 v5, v0
	ds_read_b32 v0, v3
	ds_read_b32 v12, v2
	ds_read_b32 v2, v6
	ds_read_b32 v13, v7
	ds_read_b32 v3, v10
	ds_read_b32 v10, v11
	ds_read_b32 v6, v14
	s_waitcnt lgkmcnt(6)
	v_sub_f32_e32 v0, v80, v0
	v_mul_f32_e32 v0, 0x3fb8aa3b, v0
	v_exp_f32_e32 v16, v0
	s_waitcnt lgkmcnt(4)
	v_sub_f32_e32 v0, v80, v2
	v_mul_f32_e32 v0, 0x3fb8aa3b, v0
	v_exp_f32_e32 v17, v0
	s_waitcnt lgkmcnt(2)
	v_sub_f32_e32 v0, v80, v3
	v_mul_f32_e32 v0, 0x3fb8aa3b, v0
	v_exp_f32_e32 v14, v0
	s_waitcnt lgkmcnt(0)
	v_sub_f32_e32 v0, v80, v6
	v_bfe_u32 v81, v85, 5, 1
	v_mul_f32_e32 v0, 0x3fb8aa3b, v0
	s_movk_i32 s2, 0x2080
	v_exp_f32_e32 v15, v0
	v_mad_u32_u24 v0, v81, s2, v223
	v_and_b32_e32 v3, 0x80, v85
	v_add3_u32 v65, v0, v3, v84
	v_add_u32_e32 v11, s1, v22
	ds_read_u16 v0, v65 offset:512
	ds_read_u16 v6, v65 offset:1552
	ds_read_u16 v25, v65 offset:2592
	ds_read_u16 v28, v65 offset:3632
	ds_read_u16 v23, v65 offset:2656
	ds_read_u16 v22, v65 offset:1616
	ds_read_u16 v29, v65 offset:4672
	ds_read_u16 v30, v65 offset:5712
	ds_read_u16 v3, v65 offset:6752
	ds_read_u16 v31, v65 offset:7792
	ds_read_u16 v7, v65 offset:6816
	ds_read_u16 v26, v65 offset:5776
	ds_read_u16 v27, v65 offset:4736
	ds_read_u16 v24, v65 offset:3696
	v_lshl_add_u32 v1, v83, 7, v223
	v_mul_u32_u24_e32 v2, 0x2080, v81
	v_add3_u32 v72, v1, v84, v2
	s_waitcnt lgkmcnt(10)
	v_perm_b32 v1, v28, v25, s71
	ds_read_u16 v25, v65 offset:576
	ds_read_u16 v66, v65 offset:57776
	v_perm_b32 v0, v6, v0, s71
	ds_read_u16 v6, v65 offset:7856
	ds_read_u16 v67, v65 offset:17152
	ds_read_u16 v73, v65 offset:19296
	ds_read_u16 v87, v65 offset:18256
	ds_read_u16 v103, v65 offset:17216
	s_waitcnt lgkmcnt(11)
	v_perm_b32 v3, v31, v3, s71
	v_perm_b32 v2, v30, v29, s71
	s_waitcnt lgkmcnt(4)
	v_perm_b32 v7, v6, v7, s71
	v_perm_b32 v6, v26, v27, s71
	v_pk_mul_f32 v[18:19], v[18:19], v[20:21]
	ds_read_u16 v20, v72
	ds_read_u16 v21, v72 offset:1040
	ds_read_u16 v30, v72 offset:1104
	ds_read_u16 v27, v72 offset:2080
	ds_read_u16 v31, v72 offset:2144
	ds_read_u16 v32, v72 offset:64
	ds_read_u16 v28, v72 offset:3120
	ds_read_u16 v86, v72 offset:57264
	s_waitcnt lgkmcnt(6)
	v_lshlrev_b32_e32 v21, 16, v21
	v_lshlrev_b32_e32 v20, 16, v20
	v_pk_mul_f32 v[8:9], v[4:5], v[8:9]
	s_waitcnt lgkmcnt(1)
	v_lshlrev_b32_e32 v5, 16, v28
	v_lshlrev_b32_e32 v4, 16, v27
	v_pk_mul_f32 v[20:21], v[18:19], v[20:21]
	v_pk_mul_f32 v[4:5], v[8:9], v[4:5]
	v_cvt_pk_bf16_f32 v26, v20, v21
	v_cvt_pk_bf16_f32 v27, v4, v5
	v_pk_mul_f32 v[12:13], v[12:13], v[16:17]
	ds_read_u16 v16, v72 offset:3184
	ds_read_u16 v4, v72 offset:4160
	ds_read_u16 v5, v72 offset:5200
	ds_read_u16 v20, v72 offset:5264
	ds_read_u16 v17, v72 offset:6240
	ds_read_u16 v21, v72 offset:7280
	ds_read_u16 v68, v72 offset:6304
	ds_read_u16 v33, v72 offset:4224
	s_waitcnt lgkmcnt(5)
	v_lshlrev_b32_e32 v5, 16, v5
	v_lshlrev_b32_e32 v4, 16, v4
	v_pk_mul_f32 v[4:5], v[12:13], v[4:5]
	v_or_b32_e32 v74, 0x110, v64
	v_cvt_pk_bf16_f32 v28, v4, v5
	s_waitcnt lgkmcnt(3)
	v_lshlrev_b32_e32 v4, 16, v17
	v_lshlrev_b32_e32 v17, 16, v16
	v_lshlrev_b32_e32 v16, 16, v31
	v_pk_mul_f32 v[16:17], v[8:9], v[16:17]
	v_lshlrev_b32_e32 v9, 16, v20
	s_waitcnt lgkmcnt(0)
	v_lshlrev_b32_e32 v8, 16, v33
	v_or_b32_e32 v70, 0x100, v64
	v_add_u32_e32 v75, s0, v74
	v_add_u32_e32 v77, s1, v74
	v_or_b32_e32 v74, 0x120, v64
	ds_read_b32 v11, v11
	ds_read_u16 v104, v65 offset:33792
	ds_read_u16 v105, v65 offset:35936
	ds_read_u16 v106, v65 offset:34896
	ds_read_u16 v107, v65 offset:33856
	v_pk_mul_f32 v[12:13], v[12:13], v[8:9]
	ds_read_u16 v8, v72 offset:7344
	ds_read_u16 v95, v72 offset:16640
	ds_read_u16 v108, v72 offset:17744
	ds_read_u16 v102, v72 offset:18720
	ds_read_u16 v109, v72 offset:18784
	ds_read_u16 v110, v72 offset:16704
	v_add_u32_e32 v71, s0, v70
	v_add_u32_e32 v70, s1, v70
	v_add_u32_e32 v78, s0, v74
	v_add_u32_e32 v79, s1, v74
	v_or_b32_e32 v92, 0x130, v64
	s_waitcnt lgkmcnt(5)
	v_lshlrev_b32_e32 v9, 16, v8
	v_lshlrev_b32_e32 v8, 16, v68
	ds_read_u16 v68, v65 offset:18192
	ds_read_u16 v69, v65 offset:19232
	ds_read_u16 v76, v65 offset:20272
	ds_read_u16 v111, v72 offset:17680
	ds_read_u16 v112, v72 offset:19760
	v_add_u32_e32 v88, s0, v92
	ds_read_b32 v71, v71
	ds_read_b32 v74, v70
	ds_read_b32 v70, v75
	ds_read_b32 v75, v77
	ds_read_b32 v77, v78
	ds_read_b32 v78, v79
	ds_read_b32 v79, v88
	ds_read_u16 v113, v72 offset:23984
	s_waitcnt lgkmcnt(5)
	v_sub_f32_e32 v70, v80, v70
	v_mul_f32_e32 v70, 0x3fb8aa3b, v70
	v_exp_f32_e32 v89, v70
	s_waitcnt lgkmcnt(3)
	v_sub_f32_e32 v70, v80, v77
	v_sub_f32_e32 v71, v80, v71
	v_mul_f32_e32 v70, 0x3fb8aa3b, v70
	v_mul_f32_e32 v71, 0x3fb8aa3b, v71
	v_exp_f32_e32 v90, v70
	s_waitcnt lgkmcnt(1)
	v_sub_f32_e32 v70, v80, v79
	v_exp_f32_e32 v88, v71
	v_mul_f32_e32 v70, 0x3fb8aa3b, v70
	v_or_b32_e32 v71, 0x140, v64
	v_or_b32_e32 v79, 0x150, v64
	v_exp_f32_e32 v91, v70
	v_add_u32_e32 v70, s1, v92
	v_add_u32_e32 v77, s0, v71
	v_add_u32_e32 v71, s1, v71
	v_add_u32_e32 v93, s0, v79
	v_add_u32_e32 v94, s1, v79
	v_or_b32_e32 v79, 0x160, v64
	v_or_b32_e32 v100, 0x170, v64
	v_add_u32_e32 v96, s0, v79
	v_add_u32_e32 v97, s1, v79
	v_add_u32_e32 v98, s0, v100
	ds_read_b32 v79, v70
	ds_read_b32 v70, v77
	ds_read_b32 v92, v71
	ds_read_b32 v71, v93
	ds_read_b32 v93, v94
	ds_read_b32 v77, v96
	ds_read_b32 v94, v97
	ds_read_b32 v99, v98
	s_waitcnt lgkmcnt(6)
	v_sub_f32_e32 v70, v80, v70
	v_mul_f32_e32 v70, 0x3fb8aa3b, v70
	v_exp_f32_e32 v96, v70
	s_waitcnt lgkmcnt(4)
	v_sub_f32_e32 v70, v80, v71
	v_mul_f32_e32 v70, 0x3fb8aa3b, v70
	v_exp_f32_e32 v97, v70
	s_waitcnt lgkmcnt(2)
	v_sub_f32_e32 v70, v80, v77
	v_mul_f32_e32 v70, 0x3fb8aa3b, v70
	v_exp_f32_e32 v98, v70
	s_waitcnt lgkmcnt(0)
	v_sub_f32_e32 v70, v80, v99
	v_mul_f32_e32 v70, 0x3fb8aa3b, v70
	v_exp_f32_e32 v99, v70
	v_add_u32_e32 v114, s1, v100
	ds_read_u16 v70, v65 offset:21312
	ds_read_u16 v77, v65 offset:22352
	ds_read_u16 v71, v65 offset:23392
	ds_read_u16 v100, v65 offset:24432
	ds_read_u16 v101, v65 offset:23456
	ds_read_u16 v115, v65 offset:22416
	ds_read_u16 v116, v65 offset:21376
	ds_read_u16 v117, v65 offset:20336
	s_waitcnt lgkmcnt(4)
	v_perm_b32 v71, v100, v71, s71
	v_perm_b32 v70, v77, v70, s71
	v_perm_b32 v68, v68, v67, s71
	ds_read_u16 v67, v65 offset:24496
	ds_read_u16 v118, v72 offset:33280
	ds_read_u16 v119, v72 offset:34384
	ds_read_u16 v120, v72 offset:35360
	ds_read_u16 v121, v72 offset:35424
	ds_read_u16 v122, v72 offset:33344
	s_waitcnt lgkmcnt(5)
	v_perm_b32 v77, v67, v101, s71
	v_pk_mul_f32 v[100:101], v[74:75], v[88:89]
	v_lshlrev_b32_e32 v75, 16, v111
	v_lshlrev_b32_e32 v74, 16, v95
	v_pk_mul_f32 v[10:11], v[10:11], v[14:15]
	v_lshlrev_b32_e32 v5, 16, v21
	v_pk_mul_f32 v[74:75], v[100:101], v[74:75]
	v_pk_mul_f32 v[4:5], v[10:11], v[4:5]
	v_cvt_pk_bf16_f32 v88, v74, v75
	v_pk_mul_f32 v[78:79], v[78:79], v[90:91]
	v_lshlrev_b32_e32 v75, 16, v112
	v_lshlrev_b32_e32 v74, 16, v102
	v_cvt_pk_bf16_f32 v29, v4, v5
	v_pk_mul_f32 v[74:75], v[78:79], v[74:75]
	v_perm_b32 v69, v76, v69, s71
	v_perm_b32 v76, v115, v116, s71
	v_cvt_pk_bf16_f32 v89, v74, v75
	ds_read_u16 v67, v72 offset:19824
	ds_read_u16 v74, v72 offset:20800
	ds_read_u16 v75, v72 offset:21840
	ds_read_u16 v111, v72 offset:21904
	ds_read_u16 v91, v72 offset:22880
	ds_read_u16 v112, v72 offset:23920
	ds_read_u16 v115, v72 offset:22944
	ds_read_u16 v116, v72 offset:20864
	v_pk_mul_f32 v[92:93], v[92:93], v[96:97]
	s_waitcnt lgkmcnt(5)
	v_lshlrev_b32_e32 v75, 16, v75
	v_lshlrev_b32_e32 v74, 16, v74
	v_or_b32_e32 v95, 0x210, v64
	v_pk_mul_f32 v[74:75], v[92:93], v[74:75]
	v_add_u32_e32 v97, s0, v95
	v_add_u32_e32 v102, s1, v95
	v_or_b32_e32 v95, 0x220, v64
	v_perm_b32 v5, v24, v23, s71
	v_perm_b32 v4, v22, v25, s71
	v_cvt_pk_bf16_f32 v90, v74, v75
	v_or_b32_e32 v74, 0x200, v64
	v_add_u32_e32 v123, s0, v95
	v_add_u32_e32 v124, s1, v95
	v_or_b32_e32 v125, 0x230, v64
	v_lshlrev_b32_e32 v15, 16, v30
	v_lshlrev_b32_e32 v14, 16, v32
	v_mfma_f32_32x32x16_bf16 v[48:63], v[26:29], v[0:3], 0
	v_add_u32_e32 v75, s0, v74
	v_add_u32_e32 v74, s1, v74
	v_add_u32_e32 v126, s0, v125
	ds_read_b32 v95, v114
	ds_read_b32 v114, v75
	ds_read_b32 v96, v74
	ds_read_b32 v127, v97
	ds_read_b32 v97, v102
	ds_read_b32 v123, v123
	ds_read_b32 v102, v124
	ds_read_b32 v124, v126
	v_pk_mul_f32 v[14:15], v[18:19], v[14:15]
	v_pk_mul_f32 v[18:19], v[10:11], v[8:9]
	s_waitcnt lgkmcnt(7)
	v_pk_mul_f32 v[94:95], v[94:95], v[98:99]
	v_mfma_f32_32x32x16_bf16 v[32:47], v[26:29], v[4:7], 0
	v_lshlrev_b32_e32 v75, 16, v112
	v_lshlrev_b32_e32 v74, 16, v91
	v_cvt_pk_bf16_f32 v8, v14, v15
	v_cvt_pk_bf16_f32 v9, v16, v17
	v_cvt_pk_bf16_f32 v10, v12, v13
	v_cvt_pk_bf16_f32 v11, v18, v19
	v_pk_mul_f32 v[74:75], v[94:95], v[74:75]
	v_lshlrev_b32_e32 v99, 16, v108
	v_cvt_pk_bf16_f32 v91, v74, v75
	v_lshlrev_b32_e32 v98, 16, v110
	v_mfma_f32_32x32x16_bf16 v[16:31], v[8:11], v[0:3], 0
	v_perm_b32 v75, v117, v73, s71
	v_perm_b32 v74, v87, v103, s71
	v_mul_f32_e64 v98, v100, v98
	v_mul_f32_e64 v99, v101, v99
	v_lshlrev_b32_e32 v101, 16, v67
	v_lshlrev_b32_e32 v100, 16, v109
	v_pk_mul_f32 v[78:79], v[78:79], v[100:101]
	v_lshlrev_b32_e32 v101, 16, v111
	v_mfma_f32_32x32x16_bf16 v[48:63], v[88:91], v[68:71], v[48:63]
	v_lshlrev_b32_e32 v100, 16, v116
	v_mul_f32_e64 v92, v92, v100
	v_mul_f32_e64 v93, v93, v101
	v_lshl_or_b32 v128, v81, 9, v84
	v_mfma_f32_32x32x16_bf16 v[32:47], v[88:91], v[74:77], v[32:47]
	v_lshlrev_b32_e32 v89, 16, v113
	v_lshlrev_b32_e32 v88, 16, v115
	v_mul_f32_e64 v94, v94, v88
	v_mul_f32_e64 v95, v95, v89
	v_cvt_pk_bf16_f32 v88, v98, v99
	v_cvt_pk_bf16_f32 v89, v78, v79
	v_cvt_pk_bf16_f32 v90, v92, v93
	v_cvt_pk_bf16_f32 v91, v94, v95
	v_mfma_f32_32x32x16_bf16 v[0:15], v[8:11], v[4:7], 0
	v_or_b32_e32 v93, 0x270, v64
	v_add_u32_e32 v94, s0, v93
	v_add_u32_e32 v93, s1, v93
	v_or_b32_e32 v115, 0x330, v64
	v_add_u32_e32 v116, s0, v115
	v_mfma_f32_32x32x16_bf16 v[16:31], v[88:91], v[68:71], v[16:31]
	s_waitcnt lgkmcnt(6)
	v_sub_f32_e32 v70, v80, v114
	v_mul_f32_e32 v70, 0x3fb8aa3b, v70
	v_or_b32_e32 v71, 0x240, v64
	ds_read_u16 v67, v65 offset:34832
	ds_read_u16 v68, v65 offset:35872
	ds_read_u16 v69, v65 offset:36912
	ds_read_u16 v73, v72 offset:34320
	ds_read_u16 v87, v72 offset:36400
	s_waitcnt lgkmcnt(2)
	v_perm_b32 v69, v69, v68, s71
	v_mfma_f32_32x32x16_bf16 v[0:15], v[88:91], v[74:77], v[0:15]
	v_exp_f32_e32 v74, v70
	v_sub_f32_e32 v70, v80, v127
	v_mul_f32_e32 v70, 0x3fb8aa3b, v70
	v_exp_f32_e32 v75, v70
	v_sub_f32_e32 v70, v80, v123
	v_mul_f32_e32 v70, 0x3fb8aa3b, v70
	v_exp_f32_e32 v78, v70
	v_sub_f32_e32 v70, v80, v124
	v_mul_f32_e32 v70, 0x3fb8aa3b, v70
	v_or_b32_e32 v77, 0x250, v64
	v_or_b32_e32 v89, 0x260, v64
	v_exp_f32_e32 v79, v70
	v_add_u32_e32 v70, s1, v125
	v_add_u32_e32 v76, s0, v71
	v_add_u32_e32 v71, s1, v71
	v_add_u32_e32 v88, s0, v77
	v_add_u32_e32 v77, s1, v77
	v_add_u32_e32 v92, s0, v89
	v_add_u32_e32 v89, s1, v89
	ds_read_b32 v103, v70
	ds_read_b32 v70, v76
	ds_read_b32 v90, v71
	ds_read_b32 v71, v88
	ds_read_b32 v91, v77
	ds_read_b32 v76, v92
	ds_read_b32 v92, v89
	ds_read_b32 v77, v94
	s_waitcnt lgkmcnt(6)
	v_sub_f32_e32 v70, v80, v70
	v_mul_f32_e32 v70, 0x3fb8aa3b, v70
	v_exp_f32_e32 v94, v70
	s_waitcnt lgkmcnt(4)
	v_sub_f32_e32 v70, v80, v71
	v_mul_f32_e32 v70, 0x3fb8aa3b, v70
	v_exp_f32_e32 v95, v70
	s_waitcnt lgkmcnt(2)
	v_sub_f32_e32 v70, v80, v76
	v_mul_f32_e32 v70, 0x3fb8aa3b, v70
	v_exp_f32_e32 v98, v70
	s_waitcnt lgkmcnt(0)
	v_sub_f32_e32 v70, v80, v77
	v_mul_f32_e32 v70, 0x3fb8aa3b, v70
	v_exp_f32_e32 v99, v70
	ds_read_u16 v70, v65 offset:37952
	ds_read_u16 v76, v65 offset:38992
	ds_read_u16 v71, v65 offset:40032
	ds_read_u16 v77, v65 offset:41072
	ds_read_u16 v88, v65 offset:40096
	ds_read_u16 v89, v65 offset:39056
	ds_read_u16 v100, v65 offset:38016
	ds_read_u16 v108, v65 offset:36976
	v_pk_mul_f32 v[96:97], v[96:97], v[74:75]
	v_lshlrev_b32_e32 v75, 16, v73
	v_lshlrev_b32_e32 v74, 16, v118
	v_perm_b32 v68, v67, v104, s71
	ds_read_u16 v67, v65 offset:41136
	ds_read_u16 v104, v65 offset:50432
	ds_read_u16 v109, v65 offset:52576
	ds_read_u16 v110, v65 offset:51536
	ds_read_u16 v111, v65 offset:50496
	v_pk_mul_f32 v[74:75], v[96:97], v[74:75]
	s_waitcnt lgkmcnt(9)
	v_perm_b32 v71, v77, v71, s71
	s_waitcnt lgkmcnt(4)
	v_perm_b32 v77, v67, v88, s71
	v_cvt_pk_bf16_f32 v88, v74, v75
	v_pk_mul_f32 v[78:79], v[102:103], v[78:79]
	v_lshlrev_b32_e32 v75, 16, v87
	v_lshlrev_b32_e32 v74, 16, v120
	v_pk_mul_f32 v[74:75], v[78:79], v[74:75]
	v_perm_b32 v70, v76, v70, s71
	v_perm_b32 v76, v89, v100, s71
	v_cvt_pk_bf16_f32 v89, v74, v75
	v_pk_mul_f32 v[94:95], v[90:91], v[94:95]
	ds_read_u16 v67, v72 offset:36464
	ds_read_u16 v73, v72 offset:37440
	ds_read_u16 v74, v72 offset:38480
	ds_read_u16 v87, v72 offset:38544
	ds_read_u16 v91, v72 offset:39520
	ds_read_u16 v103, v72 offset:40560
	ds_read_u16 v112, v72 offset:39584
	ds_read_u16 v113, v72 offset:37504
	s_waitcnt lgkmcnt(5)
	v_lshlrev_b32_e32 v75, 16, v74
	v_lshlrev_b32_e32 v74, 16, v73
	v_pk_mul_f32 v[74:75], v[94:95], v[74:75]
	v_or_b32_e32 v73, 0x300, v64
	v_cvt_pk_bf16_f32 v90, v74, v75
	v_or_b32_e32 v75, 0x310, v64
	v_or_b32_e32 v100, 0x320, v64
	v_add_u32_e32 v74, s0, v73
	v_add_u32_e32 v73, s1, v73
	v_add_u32_e32 v101, s0, v75
	v_add_u32_e32 v102, s0, v100
	v_add_u32_e32 v114, s1, v100
	v_add_u32_e32 v75, s1, v75
	ds_read_b32 v93, v93
	ds_read_b32 v117, v74
	ds_read_b32 v100, v73
	ds_read_b32 v73, v101
	ds_read_b32 v101, v75
	ds_read_b32 v118, v102
	ds_read_b32 v102, v114
	ds_read_b32 v114, v116
	s_waitcnt lgkmcnt(7)
	v_pk_mul_f32 v[92:93], v[92:93], v[98:99]
	v_lshlrev_b32_e32 v75, 16, v103
	v_lshlrev_b32_e32 v74, 16, v91
	v_pk_mul_f32 v[74:75], v[92:93], v[74:75]
	v_lshlrev_b32_e32 v99, 16, v119
	v_cvt_pk_bf16_f32 v91, v74, v75
	v_lshlrev_b32_e32 v98, 16, v122
	v_pk_mul_f32 v[96:97], v[96:97], v[98:99]
	v_lshlrev_b32_e32 v99, 16, v67
	v_lshlrev_b32_e32 v98, 16, v121
	v_perm_b32 v75, v108, v105, s71
	v_perm_b32 v74, v106, v107, s71
	v_pk_mul_f32 v[78:79], v[78:79], v[98:99]
	v_lshlrev_b32_e32 v99, 16, v87
	v_lshlrev_b32_e32 v98, 16, v113
	v_mfma_f32_32x32x16_bf16 v[48:63], v[88:91], v[68:71], v[48:63]
	v_mul_f32_e64 v94, v94, v98
	v_mul_f32_e64 v95, v95, v99
	ds_read_u16 v67, v72 offset:40624
	ds_read_u16 v87, v72 offset:49920
	ds_read_u16 v98, v72 offset:51024
	ds_read_u16 v99, v72 offset:52000
	ds_read_u16 v105, v72 offset:52064
	ds_read_u16 v106, v72 offset:49984
	v_mfma_f32_32x32x16_bf16 v[32:47], v[88:91], v[74:77], v[32:47]
	s_waitcnt lgkmcnt(5)
	v_lshlrev_b32_e32 v89, 16, v67
	v_lshlrev_b32_e32 v88, 16, v112
	v_mul_f32_e64 v92, v92, v88
	v_mul_f32_e64 v93, v93, v89
	v_cvt_pk_bf16_f32 v88, v96, v97
	v_cvt_pk_bf16_f32 v89, v78, v79
	v_cvt_pk_bf16_f32 v90, v94, v95
	v_cvt_pk_bf16_f32 v91, v92, v93
	v_or_b32_e32 v78, 0x350, v64
	v_add_u32_e32 v79, s0, v78
	v_mfma_f32_32x32x16_bf16 v[16:31], v[88:91], v[68:71], v[16:31]
	v_sub_f32_e32 v70, v80, v117
	v_mul_f32_e32 v70, 0x3fb8aa3b, v70
	v_or_b32_e32 v71, 0x340, v64
	ds_read_u16 v67, v65 offset:51472
	ds_read_u16 v68, v65 offset:52512
	ds_read_u16 v69, v65 offset:53552
	ds_read_u16 v96, v72 offset:50960
	ds_read_u16 v97, v72 offset:53040
	s_waitcnt lgkmcnt(2)
	v_perm_b32 v69, v69, v68, s71
	v_mfma_f32_32x32x16_bf16 v[0:15], v[88:91], v[74:77], v[0:15]
	v_exp_f32_e32 v74, v70
	v_sub_f32_e32 v70, v80, v73
	v_mul_f32_e32 v70, 0x3fb8aa3b, v70
	v_exp_f32_e32 v75, v70
	v_sub_f32_e32 v70, v80, v118
	v_mul_f32_e32 v70, 0x3fb8aa3b, v70
	v_exp_f32_e32 v76, v70
	v_sub_f32_e32 v70, v80, v114
	v_mul_f32_e32 v70, 0x3fb8aa3b, v70
	v_exp_f32_e32 v77, v70
	v_add_u32_e32 v70, s1, v115
	v_add_u32_e32 v73, s0, v71
	v_add_u32_e32 v71, s1, v71
	v_add_u32_e32 v88, s1, v78
	v_or_b32_e32 v78, 0x360, v64
	v_or_b32_e32 v64, 0x370, v64
	v_add_u32_e32 v89, s0, v78
	v_add_u32_e32 v90, s1, v78
	v_add_u32_e32 v91, s0, v64
	ds_read_b32 v103, v70
	ds_read_b32 v70, v73
	ds_read_b32 v78, v71
	ds_read_b32 v71, v79
	ds_read_b32 v79, v88
	ds_read_b32 v73, v89
	ds_read_b32 v92, v90
	ds_read_b32 v88, v91
	s_waitcnt lgkmcnt(6)
	v_sub_f32_e32 v70, v80, v70
	v_mul_f32_e32 v70, 0x3fb8aa3b, v70
	v_exp_f32_e32 v90, v70
	s_waitcnt lgkmcnt(4)
	v_sub_f32_e32 v70, v80, v71
	v_mul_f32_e32 v70, 0x3fb8aa3b, v70
	v_exp_f32_e32 v91, v70
	s_waitcnt lgkmcnt(2)
	v_sub_f32_e32 v70, v80, v73
	v_mul_f32_e32 v70, 0x3fb8aa3b, v70
	v_exp_f32_e32 v94, v70
	s_waitcnt lgkmcnt(0)
	v_sub_f32_e32 v70, v80, v88
	v_mul_f32_e32 v70, 0x3fb8aa3b, v70
	v_add_u32_e32 v64, s1, v64
	v_exp_f32_e32 v95, v70
	ds_read_b32 v93, v64
	ds_read_u16 v64, v65 offset:54592
	ds_read_u16 v70, v65 offset:55632
	ds_read_u16 v71, v65 offset:56672
	ds_read_u16 v73, v65 offset:57712
	ds_read_u16 v88, v65 offset:56736
	ds_read_u16 v89, v65 offset:55696
	ds_read_u16 v107, v65 offset:54656
	ds_read_u16 v108, v65 offset:53616
	s_waitcnt lgkmcnt(6)
	v_perm_b32 v70, v70, v64, s71
	v_pk_mul_f32 v[74:75], v[100:101], v[74:75]
	v_lshlrev_b32_e32 v65, 16, v96
	v_lshlrev_b32_e32 v64, 16, v87
	v_pk_mul_f32 v[64:65], v[74:75], v[64:65]
	v_perm_b32 v68, v67, v104, s71
	s_waitcnt lgkmcnt(3)
	v_perm_b32 v67, v66, v88, s71
	v_cvt_pk_bf16_f32 v88, v64, v65
	v_pk_mul_f32 v[76:77], v[102:103], v[76:77]
	v_lshlrev_b32_e32 v65, 16, v97
	v_lshlrev_b32_e32 v64, 16, v99
	v_pk_mul_f32 v[64:65], v[76:77], v[64:65]
	s_waitcnt lgkmcnt(1)
	v_perm_b32 v66, v89, v107, s71
	v_cvt_pk_bf16_f32 v89, v64, v65
	v_pk_mul_f32 v[78:79], v[78:79], v[90:91]
	ds_read_u16 v96, v72 offset:53104
	ds_read_u16 v64, v72 offset:54080
	ds_read_u16 v65, v72 offset:55120
	ds_read_u16 v97, v72 offset:55184
	ds_read_u16 v91, v72 offset:56160
	ds_read_u16 v99, v72 offset:57200
	ds_read_u16 v87, v72 offset:56224
	ds_read_u16 v100, v72 offset:54144
	s_waitcnt lgkmcnt(5)
	v_lshlrev_b32_e32 v65, 16, v65
	v_lshlrev_b32_e32 v64, 16, v64
	v_pk_mul_f32 v[64:65], v[78:79], v[64:65]
	v_perm_b32 v71, v73, v71, s71
	v_cvt_pk_bf16_f32 v90, v64, v65
	v_pk_mul_f32 v[72:73], v[92:93], v[94:95]
	s_waitcnt lgkmcnt(2)
	v_lshlrev_b32_e32 v65, 16, v99
	v_lshlrev_b32_e32 v64, 16, v91
	v_pk_mul_f32 v[64:65], v[72:73], v[64:65]
	v_lshlrev_b32_e32 v93, 16, v98
	v_cvt_pk_bf16_f32 v91, v64, v65
	v_lshlrev_b32_e32 v92, 16, v106
	v_perm_b32 v65, v108, v109, s71
	v_perm_b32 v64, v110, v111, s71
	v_pk_mul_f32 v[74:75], v[74:75], v[92:93]
	v_lshlrev_b32_e32 v93, 16, v96
	v_lshlrev_b32_e32 v92, 16, v105
	v_mfma_f32_32x32x16_bf16 v[48:63], v[88:91], v[68:71], v[48:63]
	v_mul_f32_e64 v76, v76, v92
	v_mul_f32_e64 v77, v77, v93
	v_lshlrev_b32_e32 v93, 16, v97
	s_waitcnt lgkmcnt(0)
	v_lshlrev_b32_e32 v92, 16, v100
	v_pk_mul_f32 v[78:79], v[78:79], v[92:93]
	s_lshl_b32 s0, s24, 3
	s_cmp_gt_i32 s23, 3
	v_mfma_f32_32x32x16_bf16 v[32:47], v[88:91], v[64:67], v[32:47]
	v_lshlrev_b32_e32 v89, 16, v86
	v_lshlrev_b32_e32 v88, 16, v87
	v_mul_f32_e64 v86, v72, v88
	v_mul_f32_e64 v87, v73, v89
	v_cvt_pk_bf16_f32 v72, v74, v75
	v_cvt_pk_bf16_f32 v73, v76, v77
	v_cvt_pk_bf16_f32 v74, v78, v79
	v_cvt_pk_bf16_f32 v75, v86, v87
	v_and_b32_e32 v76, 63, v85
	s_nop 0
	v_mfma_f32_32x32x16_bf16 v[0:15], v[72:75], v[64:67], v[0:15]
	v_lshl_add_u32 v64, v82, 2, s0
	s_cselect_b32 s0, 0x87, 3
	s_sub_i32 s0, s0, s23
	v_or_b32_e32 v67, v64, v83
	v_mov_b32_e32 v64, s0
	v_mov_b32_e32 v65, s23
	v_cndmask_b32_e32 v66, v64, v65, vcc
	ds_read_b64 v[64:65], v129 offset:232
	v_mfma_f32_32x32x16_bf16 v[16:31], v[72:75], v[68:71], v[16:31]
	s_movk_i32 s0, 0x84
	v_mad_u64_u32 v[66:67], s[0:1], v67, s0, v[66:67]
	v_ashrrev_i32_e32 v67, 31, v66
	v_lshlrev_b64 v[68:69], 13, v[66:67]
	s_waitcnt lgkmcnt(0)
	v_lshl_add_u64 v[68:69], v[64:65], 0, v[68:69]
	s_add_i32 s0, s57, 0x10400
	v_and_b32_e32 v84, 0x1c0, v206
	v_lshlrev_b32_e32 v84, 7, v84
	v_add3_u32 v82, v84, v128, s0
	v_lshl_add_u32 v83, v76, 4, v84
	v_add_u32_e32 v83, s0, v83
	v_lshlrev_b32_e32 v84, 4, v76
	s_mov_b32 s0, 0xc437000
	v_add_u32_e32 v84, s0, v84
	v_add_co_u32_e32 v68, vcc, v68, v84
	s_nop 1
	v_addc_co_u32_e32 v69, vcc, 0, v69, vcc
	v_add_co_u32_e32 v70, vcc, 0x1000, v68
	s_nop 1
	v_addc_co_u32_e32 v71, vcc, 0, v69, vcc
	v_cvt_pk_bf16_f32 v48, v48, v49
	ds_write_b16 v82, v48 offset:0
	ds_write_b16_d16_hi v82, v48 offset:128
	v_cvt_pk_bf16_f32 v50, v50, v51
	ds_write_b16 v82, v50 offset:256
	ds_write_b16_d16_hi v82, v50 offset:384
	v_cvt_pk_bf16_f32 v52, v52, v53
	ds_write_b16 v82, v52 offset:1024
	ds_write_b16_d16_hi v82, v52 offset:1152
	v_cvt_pk_bf16_f32 v54, v54, v55
	ds_write_b16 v82, v54 offset:1280
	ds_write_b16_d16_hi v82, v54 offset:1408
	v_cvt_pk_bf16_f32 v56, v56, v57
	ds_write_b16 v82, v56 offset:2048
	ds_write_b16_d16_hi v82, v56 offset:2176
	v_cvt_pk_bf16_f32 v58, v58, v59
	ds_write_b16 v82, v58 offset:2304
	ds_write_b16_d16_hi v82, v58 offset:2432
	v_cvt_pk_bf16_f32 v60, v60, v61
	ds_write_b16 v82, v60 offset:3072
	ds_write_b16_d16_hi v82, v60 offset:3200
	v_cvt_pk_bf16_f32 v62, v62, v63
	ds_write_b16 v82, v62 offset:3328
	ds_write_b16_d16_hi v82, v62 offset:3456
	v_cvt_pk_bf16_f32 v32, v32, v33
	ds_write_b16 v82, v32 offset:64
	ds_write_b16_d16_hi v82, v32 offset:192
	v_cvt_pk_bf16_f32 v34, v34, v35
	ds_write_b16 v82, v34 offset:320
	ds_write_b16_d16_hi v82, v34 offset:448
	v_cvt_pk_bf16_f32 v36, v36, v37
	ds_write_b16 v82, v36 offset:1088
	ds_write_b16_d16_hi v82, v36 offset:1216
	v_cvt_pk_bf16_f32 v38, v38, v39
	ds_write_b16 v82, v38 offset:1344
	ds_write_b16_d16_hi v82, v38 offset:1472
	v_cvt_pk_bf16_f32 v40, v40, v41
	ds_write_b16 v82, v40 offset:2112
	ds_write_b16_d16_hi v82, v40 offset:2240
	v_cvt_pk_bf16_f32 v42, v42, v43
	ds_write_b16 v82, v42 offset:2368
	ds_write_b16_d16_hi v82, v42 offset:2496
	v_cvt_pk_bf16_f32 v44, v44, v45
	ds_write_b16 v82, v44 offset:3136
	ds_write_b16_d16_hi v82, v44 offset:3264
	v_cvt_pk_bf16_f32 v46, v46, v47
	ds_write_b16 v82, v46 offset:3392
	ds_write_b16_d16_hi v82, v46 offset:3520
	v_cvt_pk_bf16_f32 v0, v0, v1
	ds_write_b16 v82, v0 offset:4160
	ds_write_b16_d16_hi v82, v0 offset:4288
	v_cvt_pk_bf16_f32 v2, v2, v3
	ds_write_b16 v82, v2 offset:4416
	ds_write_b16_d16_hi v82, v2 offset:4544
	v_cvt_pk_bf16_f32 v4, v4, v5
	ds_write_b16 v82, v4 offset:5184
	ds_write_b16_d16_hi v82, v4 offset:5312
	v_cvt_pk_bf16_f32 v6, v6, v7
	ds_write_b16 v82, v6 offset:5440
	ds_write_b16_d16_hi v82, v6 offset:5568
	v_cvt_pk_bf16_f32 v8, v8, v9
	ds_write_b16 v82, v8 offset:6208
	ds_write_b16_d16_hi v82, v8 offset:6336
	v_cvt_pk_bf16_f32 v10, v10, v11
	ds_write_b16 v82, v10 offset:6464
	ds_write_b16_d16_hi v82, v10 offset:6592
	v_cvt_pk_bf16_f32 v12, v12, v13
	ds_write_b16 v82, v12 offset:7232
	ds_write_b16_d16_hi v82, v12 offset:7360
	v_cvt_pk_bf16_f32 v14, v14, v15
	ds_write_b16 v82, v14 offset:7488
	ds_write_b16_d16_hi v82, v14 offset:7616
	v_cvt_pk_bf16_f32 v16, v16, v17
	ds_write_b16 v82, v16 offset:4096
	ds_write_b16_d16_hi v82, v16 offset:4224
	v_cvt_pk_bf16_f32 v18, v18, v19
	ds_write_b16 v82, v18 offset:4352
	ds_write_b16_d16_hi v82, v18 offset:4480
	v_cvt_pk_bf16_f32 v20, v20, v21
	ds_write_b16 v82, v20 offset:5120
	ds_write_b16_d16_hi v82, v20 offset:5248
	v_cvt_pk_bf16_f32 v22, v22, v23
	ds_write_b16 v82, v22 offset:5376
	ds_write_b16_d16_hi v82, v22 offset:5504
	v_cvt_pk_bf16_f32 v24, v24, v25
	ds_write_b16 v82, v24 offset:6144
	ds_write_b16_d16_hi v82, v24 offset:6272
	v_cvt_pk_bf16_f32 v26, v26, v27
	ds_write_b16 v82, v26 offset:6400
	ds_write_b16_d16_hi v82, v26 offset:6528
	v_cvt_pk_bf16_f32 v28, v28, v29
	ds_write_b16 v82, v28 offset:7168
	ds_write_b16_d16_hi v82, v28 offset:7296
	v_cvt_pk_bf16_f32 v30, v30, v31
	ds_write_b16 v82, v30 offset:7424
	ds_write_b16_d16_hi v82, v30 offset:7552
	ds_read_b128 v[0:3], v83 offset:0
	ds_read_b128 v[4:7], v83 offset:1024
	ds_read_b128 v[8:11], v83 offset:2048
	ds_read_b128 v[12:15], v83 offset:3072
	ds_read_b128 v[16:19], v83 offset:4096
	ds_read_b128 v[20:23], v83 offset:5120
	ds_read_b128 v[24:27], v83 offset:6144
	ds_read_b128 v[28:31], v83 offset:7168
	v_cmp_eq_u32_e32 vcc, 0, v76
	s_waitcnt lgkmcnt(7)
	global_store_dwordx4 v[68:69], v[0:3], off
	s_waitcnt lgkmcnt(6)
	global_store_dwordx4 v[68:69], v[4:7], off offset:1024
	s_waitcnt lgkmcnt(5)
	global_store_dwordx4 v[68:69], v[8:11], off offset:2048
	s_waitcnt lgkmcnt(4)
	global_store_dwordx4 v[68:69], v[12:15], off offset:3072
	s_waitcnt lgkmcnt(3)
	global_store_dwordx4 v[70:71], v[16:19], off
	s_waitcnt lgkmcnt(2)
	global_store_dwordx4 v[70:71], v[20:23], off offset:1024
	s_waitcnt lgkmcnt(1)
	global_store_dwordx4 v[70:71], v[24:27], off offset:2048
	s_waitcnt lgkmcnt(0)
	global_store_dwordx4 v[70:71], v[28:31], off offset:3072
	s_and_saveexec_b64 s[0:1], vcc
	s_cbranch_execz .LBB0_272
	v_mul_f32_e32 v0, 0x3fb8aa3b, v80
	v_exp_f32_e32 v2, v0
	v_lshl_add_u64 v[0:1], v[66:67], 2, v[64:65]
	v_add_co_u32_e32 v0, vcc, 0xe537000, v0
	s_nop 1
	v_addc_co_u32_e32 v1, vcc, 0, v1, vcc
	global_store_dword v[0:1], v2, off
	s_branch .LBB0_272
